# phase 0: attention unit-order table built by closed-form ranks over 64 lanes instead of a serial divergent 256-step merge on 16 lanes (same table)
# speedup vs baseline: 1.0087x; 1.0087x over previous
; DI void prologue(const Args& a, LAS unsigned char* lds, int gw, int NGW, int wave, int lane) {
;     ...
;     if (blockIdx.x == 0 && wave == 0 && lane < 16) {
;         const int l = lane >> 3, q = lane & 7; unsigned* tab = (unsigned*)(ws + WS_ORDER) + (l * 8 + q) * 384; int ia = 0, ic0 = 0, ic1 = 0, pos = 0;
;         int nh[2];
; #pragma unroll
;         for (int j = 0; j < 2; ++j) { const float bfv = a.in[3][l * 8 + ((2 * q + j) & 7)]; const float rate = 64.0f * __builtin_amdgcn_logf(1.0f + __builtin_amdgcn_exp2f((0.5f - bfv) * LOG2E)); float n = 82.0f / rate + 6.0f; n = n > 300.f ? 300.f : n; nh[j] = (int)n; }
;         while (ia < 128 || ic0 < 64 || ic1 < 64) {
;             const int t0 = 4 * (64 - ic0), t1 = 4 * (64 - ic1);
;             const int ca = ia < 128 ? 48 * (128 - ia) : -1, c0 = ic0 < 64 ? 24 * (t0 < nh[0] ? t0 : nh[0]) : -1, c1 = ic1 < 64 ? 24 * (t1 < nh[1] ? t1 : nh[1]) : -1;
;             if (ca >= c0 && ca >= c1) { const int qa = 127 - ia; tab[pos++] = (0u << 28) | ((unsigned)(q >> 2) << 24) | ((unsigned)(q & 3) << 16) | (unsigned)qa; ++ia; }
;             else if (c0 >= c1) { const int qc = 63 - ic0, bh = 2 * q; tab[pos++] = (2u << 28) | ((unsigned)(bh >> 3) << 24) | ((unsigned)(bh & 7) << 16) | (unsigned)qc; ++ic0; }
;             else { const int qc = 63 - ic1, bh = 2 * q + 1; tab[pos++] = (2u << 28) | ((unsigned)(bh >> 3) << 24) | ((unsigned)(bh & 7) << 16) | (unsigned)qc; ++ic1; }
;         }
.LBB0_693:
	v_readlane_b32 s0, v252, 0
	v_readlane_b32 s1, v254, 53
	s_or_b32 s0, s1, s0
	s_cmp_eq_u32 s0, 0
	s_cselect_b64 s[0:1], -1, 0
	v_cmp_gt_u32_e32 vcc, 64, v249
	s_and_b64 s[2:3], s[0:1], vcc
	s_and_saveexec_b64 s[0:1], s[2:3]
	s_cbranch_execz .LBB0_706
	v_and_b32_e32 v26, 15, v249
	v_lshlrev_b32_e32 v0, 1, v26
	v_and_b32_e32 v0, 6, v0
	v_and_or_b32 v1, v250, 8, v0
	v_lshlrev_b32_e32 v1, 2, v1
	s_waitcnt lgkmcnt(0)
	global_load_dwordx2 v[6:7], v1, s[74:75]
	s_waitcnt lgkmcnt(0)
	v_lshlrev_b32_e32 v5, 22, v26
	v_lshlrev_b32_e32 v11, 17, v26
	s_mov_b32 s4, 0x1060000
	v_lshlrev_b32_e32 v10, 16, v26
	v_bitop3_b32 v11, v11, s4, v5 bitop3:0xc8
	s_mov_b32 s4, 0x1030000
	v_mul_u32_u24_e32 v4, 0x180, v26
	v_and_b32_e32 v3, 0x1000000, v5
	v_bitop3_b32 v5, v10, s4, v5 bitop3:0xc8
	v_readlane_b32 s4, v252, 51
	v_mov_b32_e32 v9, v2
	v_lshlrev_b32_e32 v8, 2, v4
	v_readlane_b32 s5, v252, 52
	s_mov_b32 s8, 0x42a40000
	v_mov_b32_e32 v1, 0
	s_mov_b64 s[6:7], -1
	s_mov_b64 s[2:3], 0
	s_waitcnt vmcnt(0)
	v_sub_f32_e32 v6, 0.5, v6
	v_sub_f32_e32 v7, 0.5, v7
	v_mul_f32_e32 v6, 0x3fb8aa3b, v6
	v_mul_f32_e32 v7, 0x3fb8aa3b, v7
	v_exp_f32_e32 v12, v6
	v_exp_f32_e32 v13, v7
	v_lshl_add_u64 v[6:7], s[4:5], 0, v[8:9]
	v_add_f32_e32 v8, 1.0, v12
	v_add_f32_e32 v9, 1.0, v13
	v_log_f32_e32 v10, v8
	v_log_f32_e32 v12, v9
	v_or_b32_e32 v8, 0x20000000, v11
	v_or_b32_e32 v9, 0x20010000, v11
	v_mul_f32_e32 v10, 0x42800000, v10
	v_mul_f32_e32 v11, 0x42800000, v12
	v_div_scale_f32 v12, s[4:5], v10, v10, s8
	v_div_scale_f32 v14, s[4:5], v11, v11, s8
	v_rcp_f32_e32 v15, v12
	v_rcp_f32_e32 v16, v14
	v_div_scale_f32 v13, vcc, s8, v10, s8
	v_fma_f32 v18, -v12, v15, 1.0
	v_fma_f32 v19, -v14, v16, 1.0
	v_fmac_f32_e32 v15, v18, v15
	v_div_scale_f32 v17, s[4:5], s8, v11, s8
	v_fmac_f32_e32 v16, v19, v16
	v_mul_f32_e32 v18, v13, v15
	v_mul_f32_e32 v19, v17, v16
	v_fma_f32 v20, -v12, v18, v13
	v_fma_f32 v21, -v14, v19, v17
	v_fmac_f32_e32 v18, v20, v15
	v_fmac_f32_e32 v19, v21, v16
	v_fma_f32 v12, -v12, v18, v13
	v_fma_f32 v13, -v14, v19, v17
	v_div_fmas_f32 v12, v12, v15, v18
	s_mov_b64 vcc, s[4:5]
	v_div_fixup_f32 v10, v12, v10, s8
	v_div_fmas_f32 v12, v13, v16, v19
	v_add_f32_e32 v10, 0x40c00000, v10
	v_div_fixup_f32 v11, v12, v11, s8
	s_mov_b32 s4, 0x43960000
	v_cmp_nlt_f32_e32 vcc, s4, v10
	v_add_f32_e32 v11, 0x40c00000, v11
	s_mov_b64 s[8:9], -1
	v_cndmask_b32_e32 v10, v248, v10, vcc
	v_cmp_nlt_f32_e32 vcc, s4, v11
	v_cvt_i32_f32_e32 v10, v10
	s_mov_b64 s[4:5], -1
	v_cndmask_b32_e32 v11, v248, v11, vcc
	v_cvt_i32_f32_e32 v11, v11
	v_lshrrev_b32_e32 v27, 4, v249
	v_mov_b32_e32 v31, 63
	v_mov_b32_e32 v32, 0x7f
	v_cmp_gt_u32_e64 s[4:5], 2, v27
	v_cmp_eq_u32_e64 s[6:7], 3, v27
	v_and_b32_e32 v28, 1, v27
	v_lshlrev_b32_e32 v28, 6, v28
	v_cndmask_b32_e64 v28, 0, v28, s[4:5]
	v_cndmask_b32_e64 v29, v10, v11, s[6:7]
	v_cndmask_b32_e64 v30, v8, v9, s[6:7]
	v_cndmask_b32_e64 v30, v30, v5, s[4:5]
	v_cndmask_b32_e64 v31, v31, v32, s[4:5]
	s_mov_b32 s8, 0
.Lord_loop:
	v_add_u32_e32 v33, s8, v28
	v_lshlrev_b32_e32 v34, 1, v33
	v_lshlrev_b32_e32 v35, 2, v33
	v_sub_u32_e32 v34, 0x100, v34
	v_sub_u32_e32 v35, 0x100, v35
	v_min_i32_e32 v35, v35, v29
	v_cndmask_b32_e64 v34, v35, v34, s[4:5]
	v_cmp_gt_i32_e32 vcc, v10, v34
	v_cmp_gt_i32_e64 s[10:11], v11, v34
	v_cmp_ge_i32_e64 s[12:13], v10, v34
	v_sub_u32_e32 v35, 0x103, v34
	v_sub_u32_e32 v38, 0x100, v34
	v_lshrrev_b32_e32 v35, 2, v35
	v_lshrrev_b32_e32 v39, 2, v38
	v_lshrrev_b32_e32 v38, 1, v38
	v_add_u32_e32 v39, 1, v39
	v_add_u32_e32 v38, 1, v38
	v_cndmask_b32_e32 v36, 0, v35, vcc
	v_cndmask_b32_e64 v37, 0, v35, s[10:11]
	v_cndmask_b32_e64 v39, 0, v39, s[12:13]
	v_cndmask_b32_e64 v36, v38, v36, s[4:5]
	v_cndmask_b32_e64 v37, v37, v39, s[6:7]
	v_add3_u32 v36, v33, v36, v37
	v_sub_u32_e32 v37, v31, v33
	v_lshlrev_b32_e32 v36, 2, v36
	v_or_b32_e32 v37, v37, v30
	v_add_co_u32_e32 v40, vcc, v6, v36
	s_nop 1
	v_addc_co_u32_e32 v41, vcc, 0, v7, vcc
	global_store_dword v[40:41], v37, off
	s_add_i32 s8, s8, 1
	s_cmp_lt_u32 s8, 64
	s_cbranch_scc1 .Lord_loop
